# second half of the w_out weight transposition (256 items) moved from P0 to the GEMM workgroups' tail of P4 (they finish before the scan does)
# baseline (speedup 1.0000x reference)
; #define LAS __attribute__((address_space(3)))
; __device__ __forceinline__ void phase_prologue(const Args& A, LAS unsigned char* lds, int gw, int NGW, int wave, int lane) {
;     ...
;         while (it < NITEMS) {
;             const bool zero = 4 * lane >= nvalid;
; #pragma unroll
;             for (int i = 0; i < 16; ++i) *(LAS f32x4*)(tile + (wave * 16 + i) * 260 + 4 * lane) = zero ? (f32x4){0.f, 0.f, 0.f, 0.f} : cur[i];
;             bf16* dcur = dst; const int kcur = kdst;
;             const int nx = it + G_;
;             if (nx < NITEMS) { P0_DECODE(nx, src, ldw, nvalid, dst, kdst);
.LBB0_54:
	v_cmp_gt_i32_e32 vcc, s16, v70
	v_add_u32_e32 v72, s0, v69
	s_mul_i32 s10, s30, 0x410
	s_waitcnt vmcnt(0)
	v_cndmask_b32_e32 v81, 0, v39, vcc
	v_cndmask_b32_e32 v80, 0, v38, vcc
	v_cndmask_b32_e32 v79, 0, v37, vcc
	v_cndmask_b32_e32 v78, 0, v36, vcc
	ds_write_b128 v72, v[78:81]
	v_cndmask_b32_e32 v81, 0, v35, vcc
	v_cndmask_b32_e32 v80, 0, v34, vcc
	v_cndmask_b32_e32 v79, 0, v33, vcc
	v_cndmask_b32_e32 v78, 0, v32, vcc
	v_add_u32_e32 v72, s10, v69
	ds_write_b128 v72, v[78:81]
	v_cndmask_b32_e32 v81, 0, v47, vcc
	v_cndmask_b32_e32 v80, 0, v46, vcc
	v_cndmask_b32_e32 v79, 0, v45, vcc
	v_cndmask_b32_e32 v78, 0, v44, vcc
	ds_write_b128 v72, v[78:81] offset:1040
	v_cndmask_b32_e32 v81, 0, v43, vcc
	v_cndmask_b32_e32 v80, 0, v42, vcc
	v_cndmask_b32_e32 v79, 0, v41, vcc
	v_cndmask_b32_e32 v78, 0, v40, vcc
	ds_write_b128 v72, v[78:81] offset:2080
	v_cndmask_b32_e32 v81, 0, v55, vcc
	v_cndmask_b32_e32 v80, 0, v54, vcc
	v_cndmask_b32_e32 v79, 0, v53, vcc
	v_cndmask_b32_e32 v78, 0, v52, vcc
	ds_write_b128 v72, v[78:81] offset:3120
	v_cndmask_b32_e32 v81, 0, v51, vcc
	v_cndmask_b32_e32 v80, 0, v50, vcc
	v_cndmask_b32_e32 v79, 0, v49, vcc
	v_cndmask_b32_e32 v78, 0, v48, vcc
	ds_write_b128 v72, v[78:81] offset:4160
	v_cndmask_b32_e32 v81, 0, v63, vcc
	v_cndmask_b32_e32 v80, 0, v62, vcc
	v_cndmask_b32_e32 v79, 0, v61, vcc
	v_cndmask_b32_e32 v78, 0, v60, vcc
	ds_write_b128 v72, v[78:81] offset:5200
	v_cndmask_b32_e32 v81, 0, v59, vcc
	v_cndmask_b32_e32 v80, 0, v58, vcc
	v_cndmask_b32_e32 v79, 0, v57, vcc
	v_cndmask_b32_e32 v78, 0, v56, vcc
	ds_write_b128 v72, v[78:81] offset:6240
	v_cndmask_b32_e32 v81, 0, v31, vcc
	v_cndmask_b32_e32 v80, 0, v30, vcc
	v_cndmask_b32_e32 v79, 0, v29, vcc
	v_cndmask_b32_e32 v78, 0, v28, vcc
	ds_write_b128 v72, v[78:81] offset:7280
	v_cndmask_b32_e32 v81, 0, v27, vcc
	v_cndmask_b32_e32 v80, 0, v26, vcc
	v_cndmask_b32_e32 v79, 0, v25, vcc
	v_cndmask_b32_e32 v78, 0, v24, vcc
	ds_write_b128 v72, v[78:81] offset:8320
	v_cndmask_b32_e32 v81, 0, v23, vcc
	v_cndmask_b32_e32 v80, 0, v22, vcc
	v_cndmask_b32_e32 v79, 0, v21, vcc
	v_cndmask_b32_e32 v78, 0, v20, vcc
	ds_write_b128 v72, v[78:81] offset:9360
	v_cndmask_b32_e32 v81, 0, v19, vcc
	v_cndmask_b32_e32 v80, 0, v18, vcc
	v_cndmask_b32_e32 v79, 0, v17, vcc
	v_cndmask_b32_e32 v78, 0, v16, vcc
	ds_write_b128 v72, v[78:81] offset:10400
	v_cndmask_b32_e32 v81, 0, v15, vcc
	v_cndmask_b32_e32 v80, 0, v14, vcc
	v_cndmask_b32_e32 v79, 0, v13, vcc
	v_cndmask_b32_e32 v78, 0, v12, vcc
	s_add_i32 s81, s81, s70
	s_cmpk_lt_i32 s81, 0x840
	s_cbranch_scc1 .Lp0_noskip
	s_sub_i32 s99, s81, s70
	s_cmpk_lt_i32 s99, 0x840
	s_cbranch_scc0 .Lp0_noskip
	s_addk_i32 s81, 0x100
	s_add_i32 s78, s78, 0x10000
	s_addk_i32 s80, 0x1000
	s_addk_i32 s75, 0x800

; #define GAS __attribute__((address_space(1)))
; #define LAS __attribute__((address_space(3)))
; #define LDS_WAIT() asm volatile("s_waitcnt lgkmcnt(0)" ::: "memory")
; __device__ __forceinline__ unsigned pk2(float lo, float hi) { return f2bf(lo) | (f2bf(hi) << 16); }
; __device__ __forceinline__ void phase_prologue(const Args& A, LAS unsigned char* lds, int gw, int NGW, int wave, int lane) {
;     ...
;             { const int n = wave * 32 + (lane & 31);
; #pragma unroll
;               for (int i = 0; i < 8; ++i) { const int c = (lane >> 5) + 2 * i; const LAS float* tp = tile + (8 * c) * 260 + n;
;                   v4u o; o.x = pk2(tp[0], tp[260]); o.y = pk2(tp[2 * 260], tp[3 * 260]); o.z = pk2(tp[4 * 260], tp[5 * 260]); o.w = pk2(tp[6 * 260], tp[7 * 260]);
;                   *(GAS v4u*)(dcur + (size_t)n * kcur + 8 * c) = o; } }
;             LDS_WAIT(); __syncthreads();
;             it = nx;
.LBB0_578:
	s_waitcnt vmcnt(0)
	s_mov_b64 s[56:57], s[36:37]
	s_barrier
	s_load_dword s0, s[62:63], 0xb8
	s_waitcnt lgkmcnt(0)
	s_mov_b32 s2, s97
	s_mov_b32 s3, s0
	s_cmpk_lg_i32 s0, 0x100
	s_cbranch_scc1 .Lwo_idx
	s_and_b32 s1, s97, 7
	s_lshr_b32 s2, s97, 3
	s_sub_u32 s2, s2, 12
	s_mul_i32 s1, s1, 20
	s_add_i32 s2, s2, s1
	s_movk_i32 s3, 0xa0
.Lwo_idx:
	s_mov_b32 s98, s3
	s_add_i32 s99, s2, 0x100
	s_load_dwordx2 s[4:5], s[62:63], 0x88
	v_mbcnt_lo_u32_b32 v64, -1, 0
	v_mbcnt_hi_u32_b32 v64, -1, v64
	v_readlane_b32 s0, v254, 8
	s_nop 3
	s_lshr_b32 s0, s0, 6
	v_lshlrev_b32_e32 v65, 4, v64
	s_lshl_b32 s1, s0, 18
	v_add_u32_e32 v65, s1, v65
	s_mul_i32 s1, s0, 0x4100
	v_lshlrev_b32_e32 v66, 4, v64
	v_add_u32_e32 v66, s1, v66
	v_and_b32_e32 v67, 31, v64
	s_lshl_b32 s1, s0, 5
	v_add_u32_e32 v67, s1, v67
	v_lshrrev_b32_e32 v68, 5, v64
	v_mul_u32_u24_e32 v69, 0x2080, v68
	v_lshl_add_u32 v69, v67, 2, v69
	v_add_u32_e32 v70, 0x10400, v69
	v_lshlrev_b32_e32 v71, 13, v67
	v_lshl_add_u32 v71, v68, 4, v71
	s_mov_b32 s2, s99
	s_waitcnt lgkmcnt(0)
	s_cmpk_lt_u32 s2, 0x200
	s_cbranch_scc0 .Lwo_done
.Lwo_item:
	s_lshr_b32 s6, s2, 4
	s_and_b32 s7, s2, 15
	s_lshl_b32 s8, s6, 21
	s_lshl_b32 s9, s7, 10
	s_add_u32 s8, s8, s9
	s_add_u32 s20, s4, s8
	s_addc_u32 s21, s5, 0
	s_lshl_b32 s8, s7, 21
	s_lshl_b32 s9, s6, 8
	s_add_u32 s8, s8, s9
	s_add_u32 s8, s8, 0xb500000
	s_add_u32 s22, s34, s8
	s_addc_u32 s23, s35, 0
	global_load_dwordx4 v[0:3], v65, s[20:21] nt
	s_add_u32 s20, s20, 0x4000
	s_addc_u32 s21, s21, 0
	global_load_dwordx4 v[4:7], v65, s[20:21] nt
	s_add_u32 s20, s20, 0x4000
	s_addc_u32 s21, s21, 0
	global_load_dwordx4 v[8:11], v65, s[20:21] nt
	s_add_u32 s20, s20, 0x4000
	s_addc_u32 s21, s21, 0
	global_load_dwordx4 v[12:15], v65, s[20:21] nt
	s_add_u32 s20, s20, 0x4000
	s_addc_u32 s21, s21, 0
	global_load_dwordx4 v[16:19], v65, s[20:21] nt
	s_add_u32 s20, s20, 0x4000
	s_addc_u32 s21, s21, 0
	global_load_dwordx4 v[20:23], v65, s[20:21] nt
	s_add_u32 s20, s20, 0x4000
	s_addc_u32 s21, s21, 0
	global_load_dwordx4 v[24:27], v65, s[20:21] nt
	s_add_u32 s20, s20, 0x4000
	s_addc_u32 s21, s21, 0
	global_load_dwordx4 v[28:31], v65, s[20:21] nt
	s_add_u32 s20, s20, 0x4000
	s_addc_u32 s21, s21, 0
	global_load_dwordx4 v[32:35], v65, s[20:21] nt
	s_add_u32 s20, s20, 0x4000
	s_addc_u32 s21, s21, 0
	global_load_dwordx4 v[36:39], v65, s[20:21] nt
	s_add_u32 s20, s20, 0x4000
	s_addc_u32 s21, s21, 0
	global_load_dwordx4 v[40:43], v65, s[20:21] nt
	s_add_u32 s20, s20, 0x4000
	s_addc_u32 s21, s21, 0
	global_load_dwordx4 v[44:47], v65, s[20:21] nt
	s_add_u32 s20, s20, 0x4000
	s_addc_u32 s21, s21, 0
	global_load_dwordx4 v[48:51], v65, s[20:21] nt
	s_add_u32 s20, s20, 0x4000
	s_addc_u32 s21, s21, 0
	global_load_dwordx4 v[52:55], v65, s[20:21] nt
	s_add_u32 s20, s20, 0x4000
	s_addc_u32 s21, s21, 0
	global_load_dwordx4 v[56:59], v65, s[20:21] nt
	s_add_u32 s20, s20, 0x4000
	s_addc_u32 s21, s21, 0
	global_load_dwordx4 v[60:63], v65, s[20:21] nt
	s_waitcnt vmcnt(15)
	ds_write_b128 v66, v[0:3]
	s_waitcnt vmcnt(14)
	ds_write_b128 v66, v[4:7] offset:1040
	s_waitcnt vmcnt(13)
	ds_write_b128 v66, v[8:11] offset:2080
	s_waitcnt vmcnt(12)
	ds_write_b128 v66, v[12:15] offset:3120
	s_waitcnt vmcnt(11)
	ds_write_b128 v66, v[16:19] offset:4160
	s_waitcnt vmcnt(10)
	ds_write_b128 v66, v[20:23] offset:5200
	s_waitcnt vmcnt(9)
	ds_write_b128 v66, v[24:27] offset:6240
	s_waitcnt vmcnt(8)
	ds_write_b128 v66, v[28:31] offset:7280
	s_waitcnt vmcnt(7)
	ds_write_b128 v66, v[32:35] offset:8320
	s_waitcnt vmcnt(6)
	ds_write_b128 v66, v[36:39] offset:9360
	s_waitcnt vmcnt(5)
	ds_write_b128 v66, v[40:43] offset:10400
	s_waitcnt vmcnt(4)
	ds_write_b128 v66, v[44:47] offset:11440
	s_waitcnt vmcnt(3)
	ds_write_b128 v66, v[48:51] offset:12480
	s_waitcnt vmcnt(2)
	ds_write_b128 v66, v[52:55] offset:13520
	s_waitcnt vmcnt(1)
	ds_write_b128 v66, v[56:59] offset:14560
	s_waitcnt vmcnt(0)
	ds_write_b128 v66, v[60:63] offset:15600
	s_waitcnt lgkmcnt(0)
	s_barrier
; #define GAS __attribute__((address_space(1)))
; #define LAS __attribute__((address_space(3)))
; #define LDS_WAIT() asm volatile("s_waitcnt lgkmcnt(0)" ::: "memory")
; __device__ __forceinline__ unsigned pk2(float lo, float hi) { return f2bf(lo) | (f2bf(hi) << 16); }
; __device__ __forceinline__ unsigned xb_add(unsigned* p, unsigned v) { return __hip_atomic_fetch_add(p, v, __ATOMIC_RELAXED, __HIP_MEMORY_SCOPE_AGENT); }
; __device__ __forceinline__ void xcd_barrier(const XcdBarrier& b, int tid_now) {
;     asm volatile("s_waitcnt vmcnt(0)" ::: "memory");
;     __syncthreads();
;     if (tid_now == 0) {
;         unsigned* bar = b.bar;
;         __builtin_amdgcn_s_waitcnt(0);
;         unsigned nloc = b.st[0], nx = b.st[1];
;         if (nloc == 0u) { xcd_barrier_complete(bar, b.x, nloc, nx); b.st[0] = nloc; b.st[1] = nx; }
;         const unsigned old = xb_add(&bar[XB_XSUB(b.x)], 1u);
; __device__ __forceinline__ void phase_prologue(const Args& A, LAS unsigned char* lds, int gw, int NGW, int wave, int lane) {
;     ...
;             { const int n = wave * 32 + (lane & 31);
; #pragma unroll
;               for (int i = 0; i < 8; ++i) { const int c = (lane >> 5) + 2 * i; const LAS float* tp = tile + (8 * c) * 260 + n;
;                   v4u o; o.x = pk2(tp[0], tp[260]); o.y = pk2(tp[2 * 260], tp[3 * 260]); o.z = pk2(tp[4 * 260], tp[5 * 260]); o.w = pk2(tp[6 * 260], tp[7 * 260]);
;                   *(GAS v4u*)(dcur + (size_t)n * kcur + 8 * c) = o; } }
;             LDS_WAIT(); __syncthreads();
	ds_read_b32 v72, v69
	ds_read_b32 v73, v69 offset:1040
	ds_read_b32 v74, v69 offset:2080
	ds_read_b32 v75, v69 offset:3120
	ds_read_b32 v76, v69 offset:4160
	ds_read_b32 v77, v69 offset:5200
	ds_read_b32 v78, v69 offset:6240
	ds_read_b32 v79, v69 offset:7280
	ds_read_b32 v80, v69 offset:16640
	ds_read_b32 v81, v69 offset:17680
	ds_read_b32 v82, v69 offset:18720
	ds_read_b32 v83, v69 offset:19760
	ds_read_b32 v84, v69 offset:20800
	ds_read_b32 v85, v69 offset:21840
	ds_read_b32 v86, v69 offset:22880
	ds_read_b32 v87, v69 offset:23920
	s_waitcnt lgkmcnt(8)
	v_cvt_pk_bf16_f32 v136, v72, v73
	v_cvt_pk_bf16_f32 v137, v74, v75
	v_cvt_pk_bf16_f32 v138, v76, v77
	v_cvt_pk_bf16_f32 v139, v78, v79
	global_store_dwordx4 v71, v[136:139], s[22:23] nt
	ds_read_b32 v88, v69 offset:33280
	ds_read_b32 v89, v69 offset:34320
	ds_read_b32 v90, v69 offset:35360
	ds_read_b32 v91, v69 offset:36400
	ds_read_b32 v92, v69 offset:37440
	ds_read_b32 v93, v69 offset:38480
	ds_read_b32 v94, v69 offset:39520
	ds_read_b32 v95, v69 offset:40560
	s_waitcnt lgkmcnt(8)
	v_cvt_pk_bf16_f32 v140, v80, v81
	v_cvt_pk_bf16_f32 v141, v82, v83
	v_cvt_pk_bf16_f32 v142, v84, v85
	v_cvt_pk_bf16_f32 v143, v86, v87
	global_store_dwordx4 v71, v[140:143], s[22:23] offset:32 nt
	ds_read_b32 v96, v69 offset:49920
	ds_read_b32 v97, v69 offset:50960
	ds_read_b32 v98, v69 offset:52000
	ds_read_b32 v99, v69 offset:53040
	ds_read_b32 v100, v69 offset:54080
	ds_read_b32 v101, v69 offset:55120
	ds_read_b32 v102, v69 offset:56160
	ds_read_b32 v103, v69 offset:57200
	s_waitcnt lgkmcnt(8)
	v_cvt_pk_bf16_f32 v136, v88, v89
	v_cvt_pk_bf16_f32 v137, v90, v91
	v_cvt_pk_bf16_f32 v138, v92, v93
	v_cvt_pk_bf16_f32 v139, v94, v95
	global_store_dwordx4 v71, v[136:139], s[22:23] offset:64 nt
	ds_read_b32 v104, v70
	ds_read_b32 v105, v70 offset:1040
	ds_read_b32 v106, v70 offset:2080
	ds_read_b32 v107, v70 offset:3120
	ds_read_b32 v108, v70 offset:4160
	ds_read_b32 v109, v70 offset:5200
	ds_read_b32 v110, v70 offset:6240
	ds_read_b32 v111, v70 offset:7280
	s_waitcnt lgkmcnt(8)
	v_cvt_pk_bf16_f32 v140, v96, v97
	v_cvt_pk_bf16_f32 v141, v98, v99
	v_cvt_pk_bf16_f32 v142, v100, v101
	v_cvt_pk_bf16_f32 v143, v102, v103
	global_store_dwordx4 v71, v[140:143], s[22:23] offset:96 nt
	ds_read_b32 v112, v70 offset:16640
	ds_read_b32 v113, v70 offset:17680
	ds_read_b32 v114, v70 offset:18720
	ds_read_b32 v115, v70 offset:19760
	ds_read_b32 v116, v70 offset:20800
	ds_read_b32 v117, v70 offset:21840
	ds_read_b32 v118, v70 offset:22880
	ds_read_b32 v119, v70 offset:23920
	s_waitcnt lgkmcnt(8)
	v_cvt_pk_bf16_f32 v136, v104, v105
	v_cvt_pk_bf16_f32 v137, v106, v107
	v_cvt_pk_bf16_f32 v138, v108, v109
	v_cvt_pk_bf16_f32 v139, v110, v111
	global_store_dwordx4 v71, v[136:139], s[22:23] offset:128 nt
	ds_read_b32 v120, v70 offset:33280
	ds_read_b32 v121, v70 offset:34320
	ds_read_b32 v122, v70 offset:35360
	ds_read_b32 v123, v70 offset:36400
	ds_read_b32 v124, v70 offset:37440
	ds_read_b32 v125, v70 offset:38480
	ds_read_b32 v126, v70 offset:39520
	ds_read_b32 v127, v70 offset:40560
	s_waitcnt lgkmcnt(8)
	v_cvt_pk_bf16_f32 v140, v112, v113
	v_cvt_pk_bf16_f32 v141, v114, v115
	v_cvt_pk_bf16_f32 v142, v116, v117
	v_cvt_pk_bf16_f32 v143, v118, v119
	global_store_dwordx4 v71, v[140:143], s[22:23] offset:160 nt
	ds_read_b32 v128, v70 offset:49920
	ds_read_b32 v129, v70 offset:50960
	ds_read_b32 v130, v70 offset:52000
	ds_read_b32 v131, v70 offset:53040
	ds_read_b32 v132, v70 offset:54080
	ds_read_b32 v133, v70 offset:55120
	ds_read_b32 v134, v70 offset:56160
	ds_read_b32 v135, v70 offset:57200
	s_waitcnt lgkmcnt(8)
	v_cvt_pk_bf16_f32 v136, v120, v121
	v_cvt_pk_bf16_f32 v137, v122, v123
	v_cvt_pk_bf16_f32 v138, v124, v125
	v_cvt_pk_bf16_f32 v139, v126, v127
	global_store_dwordx4 v71, v[136:139], s[22:23] offset:192 nt
	s_waitcnt lgkmcnt(0)
	v_cvt_pk_bf16_f32 v140, v128, v129
	v_cvt_pk_bf16_f32 v141, v130, v131
	v_cvt_pk_bf16_f32 v142, v132, v133
	v_cvt_pk_bf16_f32 v143, v134, v135
	global_store_dwordx4 v71, v[140:143], s[22:23] offset:224 nt
	s_barrier
	s_add_i32 s2, s2, s98
	s_cmpk_lt_u32 s2, 0x200
	s_cbranch_scc1 .Lwo_item
.Lwo_done:
.LBB0_579:
	s_cmp_gt_i32 s57, 5
	s_cselect_b64 s[2:3], -1, 0
	s_and_b64 s[0:1], s[10:11], s[2:3]
	s_andn2_b64 vcc, exec, s[0:1]
	s_cbranch_vccnz .LBB0_633
	v_readlane_b32 s0, v254, 8
	s_waitcnt vmcnt(0)
	v_mbcnt_lo_u32_b32 v0, -1, 0
	v_mbcnt_hi_u32_b32 v0, -1, v0
	s_waitcnt vmcnt(0)
	s_andn2_b32 s0, s0, 63
	v_sub_u32_e32 v0, 0, v0
	v_cmp_eq_u32_e32 vcc, s0, v0
	s_waitcnt lgkmcnt(0)
	s_barrier
	s_and_saveexec_b64 s[4:5], vcc
	s_cbranch_execz .LBB0_632
	s_add_i32 s0, 0, 0x27f20
	v_mov_b32_e32 v0, s0
	s_waitcnt vmcnt(0) expcnt(0) lgkmcnt(0)
	ds_read_b32 v2, v0
	s_add_i32 s0, 0, 0x27f24
	v_mov_b32_e32 v0, s0
	ds_read_b32 v0, v0
	s_waitcnt lgkmcnt(1)
	v_cmp_ne_u32_e32 vcc, 0, v2
	s_cbranch_vccnz .LBB0_596
	s_load_dwordx2 s[0:1], s[62:63], 0xb8
	s_load_dword s9, s[62:63], 0xc0
	s_add_u32 s6, s34, 0x4200
	s_addc_u32 s7, s35, 0
	s_add_u32 s8, s34, 0x4400
	s_waitcnt lgkmcnt(0)
	s_mul_i32 s0, s1, s0
	s_mul_i32 s0, s0, s9
	s_addc_u32 s9, s35, 0
	s_add_u32 s10, s34, 0x4500
	s_addc_u32 s11, s35, 0
	s_add_u32 s12, s34, 0x4600
	s_addc_u32 s13, s35, 0
	s_add_u32 s14, s34, 0x4700
	s_addc_u32 s15, s35, 0
	s_add_u32 s16, s34, 0x4800
	s_addc_u32 s17, s35, 0
	s_add_u32 s20, s34, 0x4900
	s_addc_u32 s21, s35, 0
	s_add_u32 s22, s34, 0x4a00
	s_addc_u32 s23, s35, 0
	s_add_u32 s30, s34, 0x4b00
	s_addc_u32 s31, s35, 0
	s_add_u32 s38, s34, 0x4c00
	s_addc_u32 s39, s35, 0
	s_add_u32 s40, s34, 0x4d00
	s_addc_u32 s41, s35, 0
	s_add_u32 s42, s34, 0x4e00
	s_addc_u32 s43, s35, 0
	s_add_u32 s46, s34, 0x4f00
	s_addc_u32 s47, s35, 0
	s_add_u32 s48, s34, 0x5000
	s_addc_u32 s49, s35, 0
	s_add_u32 s50, s34, 0x5100
	s_addc_u32 s51, s35, 0
	s_add_u32 s52, s34, 0x5200
	s_addc_u32 s53, s35, 0
	s_add_u32 s54, s34, 0x5300
	s_mov_b64 s[24:25], s[56:57]
	s_addc_u32 s55, s35, 0
	s_mov_b32 s1, 1
	v_mov_b32_e32 v16, 0
	s_branch .LBB0_584
